# FFN K-loops: in every load segment the LDS-DMA group (SALU addresses, m0, global_load_lds) is issued first and the ds_read_b128 fragment reads after it (same instructions, same bytes)
# baseline (speedup 1.0000x reference)
.LBB0_182:
	s_add_u32 s30, s72, 0xfff00080
	s_addc_u32 s31, s73, -1
	s_cmp_eq_u32 s41, 60
	s_cselect_b32 s31, s13, s31
	s_cselect_b32 s30, s37, s30
	s_cselect_b32 s75, s11, s40
	s_cselect_b32 s74, s38, s39
	s_add_i32 m0, s29, 0xc000
	s_nop 0
	global_load_lds_dwordx4 v136, s[72:73]
	s_add_i32 m0, s29, 0xe000
	s_nop 0
	global_load_lds_dwordx4 v138, s[72:73]
	ds_read_b128 v[144:147], v153 offset:0
	ds_read_b128 v[156:159], v153 offset:1024
	ds_read_b128 v[160:163], v153 offset:2048
	ds_read_b128 v[164:167], v153 offset:3072
	ds_read_b128 v[168:171], v154 offset:0
	ds_read_b128 v[172:175], v154 offset:1024
	ds_read_b128 v[176:179], v154 offset:2048
	ds_read_b128 v[180:183], v154 offset:3072
	ds_read_b128 v[184:187], v155 offset:0
	ds_read_b128 v[188:191], v155 offset:1024
	ds_read_b128 v[192:195], v155 offset:2048
	ds_read_b128 v[196:199], v155 offset:3072
	ds_read_b128 v[200:203], v155 offset:4096
	ds_read_b128 v[204:207], v155 offset:5120
	ds_read_b128 v[208:211], v155 offset:6144
	ds_read_b128 v[212:215], v155 offset:7168
	s_waitcnt vmcnt(8)
	s_waitcnt lgkmcnt(0)
	s_barrier
	v_mfma_f32_16x16x32_bf16 v[124:127], v[144:147], v[184:187], v[124:127]
	v_mfma_f32_16x16x32_bf16 v[120:123], v[160:163], v[184:187], v[120:123]
	v_mfma_f32_16x16x32_bf16 v[108:111], v[144:147], v[192:195], v[108:111]
	v_mfma_f32_16x16x32_bf16 v[104:107], v[160:163], v[192:195], v[104:107]
	v_mfma_f32_16x16x32_bf16 v[92:95], v[144:147], v[200:203], v[92:95]
	v_mfma_f32_16x16x32_bf16 v[88:91], v[160:163], v[200:203], v[88:91]
	v_mfma_f32_16x16x32_bf16 v[76:79], v[144:147], v[208:211], v[76:79]
	v_mfma_f32_16x16x32_bf16 v[72:75], v[160:163], v[208:211], v[72:75]
	v_mfma_f32_16x16x32_bf16 v[124:127], v[156:159], v[188:191], v[124:127]
	v_mfma_f32_16x16x32_bf16 v[120:123], v[164:167], v[188:191], v[120:123]
	v_mfma_f32_16x16x32_bf16 v[108:111], v[156:159], v[196:199], v[108:111]
	v_mfma_f32_16x16x32_bf16 v[104:107], v[164:167], v[196:199], v[104:107]
	v_mfma_f32_16x16x32_bf16 v[92:95], v[156:159], v[204:207], v[92:95]
	v_mfma_f32_16x16x32_bf16 v[88:91], v[164:167], v[204:207], v[88:91]
	v_mfma_f32_16x16x32_bf16 v[76:79], v[156:159], v[212:215], v[76:79]
	v_mfma_f32_16x16x32_bf16 v[72:75], v[164:167], v[212:215], v[72:75]
	v_mfma_f32_16x16x32_bf16 v[116:119], v[168:171], v[184:187], v[116:119]
	v_mfma_f32_16x16x32_bf16 v[112:115], v[176:179], v[184:187], v[112:115]
	v_mfma_f32_16x16x32_bf16 v[100:103], v[168:171], v[192:195], v[100:103]
	v_mfma_f32_16x16x32_bf16 v[96:99], v[176:179], v[192:195], v[96:99]
	v_mfma_f32_16x16x32_bf16 v[84:87], v[168:171], v[200:203], v[84:87]
	v_mfma_f32_16x16x32_bf16 v[80:83], v[176:179], v[200:203], v[80:83]
	v_mfma_f32_16x16x32_bf16 v[68:71], v[168:171], v[208:211], v[68:71]
	v_mfma_f32_16x16x32_bf16 v[64:67], v[176:179], v[208:211], v[64:67]
	v_mfma_f32_16x16x32_bf16 v[116:119], v[172:175], v[188:191], v[116:119]
	v_mfma_f32_16x16x32_bf16 v[112:115], v[180:183], v[188:191], v[112:115]
	v_mfma_f32_16x16x32_bf16 v[100:103], v[172:175], v[196:199], v[100:103]
	v_mfma_f32_16x16x32_bf16 v[96:99], v[180:183], v[196:199], v[96:99]
	v_mfma_f32_16x16x32_bf16 v[84:87], v[172:175], v[204:207], v[84:87]
	v_mfma_f32_16x16x32_bf16 v[80:83], v[180:183], v[204:207], v[80:83]
	v_mfma_f32_16x16x32_bf16 v[68:71], v[172:175], v[212:215], v[68:71]
	v_mfma_f32_16x16x32_bf16 v[64:67], v[180:183], v[212:215], v[64:67]
	s_barrier
	s_add_u32 s42, s74, 0x100000
	s_addc_u32 s43, s75, 0
	s_add_i32 m0, s29, 0x10000
	s_nop 0
	global_load_lds_dwordx4 v130, s[74:75]
	s_add_i32 m0, s29, 0x12000
	s_nop 0
	global_load_lds_dwordx4 v134, s[74:75]
	s_add_i32 m0, s29, 0x14000
	s_nop 0
	global_load_lds_dwordx4 v130, s[42:43]
	s_add_i32 m0, s29, 0x16000
	s_nop 0
	global_load_lds_dwordx4 v134, s[42:43]
	s_add_i32 m0, s29, 0x0
	s_nop 0
	global_load_lds_dwordx4 v128, s[30:31]
	s_add_i32 m0, s29, 0x2000
	s_nop 0
	global_load_lds_dwordx4 v132, s[30:31]
	ds_read_b128 v[184:187], v155 offset:16384
	ds_read_b128 v[188:191], v155 offset:17408
	ds_read_b128 v[192:195], v155 offset:18432
	ds_read_b128 v[196:199], v155 offset:19456
	ds_read_b128 v[200:203], v155 offset:20480
	ds_read_b128 v[204:207], v155 offset:21504
	ds_read_b128 v[208:211], v155 offset:22528
	ds_read_b128 v[212:215], v155 offset:23552
	s_waitcnt vmcnt(8)
	s_waitcnt lgkmcnt(0)
	s_barrier
	v_mfma_f32_16x16x32_bf16 v[60:63], v[144:147], v[184:187], v[60:63]
	v_mfma_f32_16x16x32_bf16 v[56:59], v[160:163], v[184:187], v[56:59]
	v_mfma_f32_16x16x32_bf16 v[44:47], v[144:147], v[192:195], v[44:47]
	v_mfma_f32_16x16x32_bf16 v[40:43], v[160:163], v[192:195], v[40:43]
	v_mfma_f32_16x16x32_bf16 v[28:31], v[144:147], v[200:203], v[28:31]
	v_mfma_f32_16x16x32_bf16 v[24:27], v[160:163], v[200:203], v[24:27]
	v_mfma_f32_16x16x32_bf16 v[12:15], v[144:147], v[208:211], v[12:15]
	v_mfma_f32_16x16x32_bf16 v[8:11], v[160:163], v[208:211], v[8:11]
	v_mfma_f32_16x16x32_bf16 v[60:63], v[156:159], v[188:191], v[60:63]
	v_mfma_f32_16x16x32_bf16 v[56:59], v[164:167], v[188:191], v[56:59]
	v_mfma_f32_16x16x32_bf16 v[44:47], v[156:159], v[196:199], v[44:47]
	v_mfma_f32_16x16x32_bf16 v[40:43], v[164:167], v[196:199], v[40:43]
	v_mfma_f32_16x16x32_bf16 v[28:31], v[156:159], v[204:207], v[28:31]
	v_mfma_f32_16x16x32_bf16 v[24:27], v[164:167], v[204:207], v[24:27]
	v_mfma_f32_16x16x32_bf16 v[12:15], v[156:159], v[212:215], v[12:15]
	v_mfma_f32_16x16x32_bf16 v[8:11], v[164:167], v[212:215], v[8:11]
	v_mfma_f32_16x16x32_bf16 v[52:55], v[168:171], v[184:187], v[52:55]
	v_mfma_f32_16x16x32_bf16 v[48:51], v[176:179], v[184:187], v[48:51]
	v_mfma_f32_16x16x32_bf16 v[36:39], v[168:171], v[192:195], v[36:39]
	v_mfma_f32_16x16x32_bf16 v[32:35], v[176:179], v[192:195], v[32:35]
	v_mfma_f32_16x16x32_bf16 v[20:23], v[168:171], v[200:203], v[20:23]
	v_mfma_f32_16x16x32_bf16 v[16:19], v[176:179], v[200:203], v[16:19]
	v_mfma_f32_16x16x32_bf16 v[4:7], v[168:171], v[208:211], v[4:7]
	v_mfma_f32_16x16x32_bf16 v[0:3], v[176:179], v[208:211], v[0:3]
	v_mfma_f32_16x16x32_bf16 v[52:55], v[172:175], v[188:191], v[52:55]
	v_mfma_f32_16x16x32_bf16 v[48:51], v[180:183], v[188:191], v[48:51]
	v_mfma_f32_16x16x32_bf16 v[36:39], v[172:175], v[196:199], v[36:39]
	v_mfma_f32_16x16x32_bf16 v[32:35], v[180:183], v[196:199], v[32:35]
	v_mfma_f32_16x16x32_bf16 v[20:23], v[172:175], v[204:207], v[20:23]
	v_mfma_f32_16x16x32_bf16 v[16:19], v[180:183], v[204:207], v[16:19]
	v_mfma_f32_16x16x32_bf16 v[4:7], v[172:175], v[212:215], v[4:7]
	v_mfma_f32_16x16x32_bf16 v[0:3], v[180:183], v[212:215], v[0:3]
	s_barrier
	s_add_u32 s98, s30, 0x100000
	s_addc_u32 s99, s31, 0
	s_add_i32 m0, s29, 0x4000
	s_nop 0
	global_load_lds_dwordx4 v128, s[98:99]
	s_add_i32 m0, s29, 0x6000
	s_nop 0
	global_load_lds_dwordx4 v132, s[98:99]
	ds_read_b128 v[144:147], v153 offset:32768
	ds_read_b128 v[156:159], v153 offset:33792
	ds_read_b128 v[160:163], v153 offset:34816
	ds_read_b128 v[164:167], v153 offset:35840
	ds_read_b128 v[168:171], v154 offset:32768
	ds_read_b128 v[172:175], v154 offset:33792
	ds_read_b128 v[176:179], v154 offset:34816
	ds_read_b128 v[180:183], v154 offset:35840
	ds_read_b128 v[184:187], v155 offset:32768
	ds_read_b128 v[188:191], v155 offset:33792
	ds_read_b128 v[192:195], v155 offset:34816
	ds_read_b128 v[196:199], v155 offset:35840
	ds_read_b128 v[200:203], v155 offset:36864
	ds_read_b128 v[204:207], v155 offset:37888
	ds_read_b128 v[208:211], v155 offset:38912
	ds_read_b128 v[212:215], v155 offset:39936
	s_waitcnt vmcnt(8)
	s_waitcnt lgkmcnt(0)
	s_barrier
	v_mfma_f32_16x16x32_bf16 v[124:127], v[144:147], v[184:187], v[124:127]
	v_mfma_f32_16x16x32_bf16 v[120:123], v[160:163], v[184:187], v[120:123]
	v_mfma_f32_16x16x32_bf16 v[108:111], v[144:147], v[192:195], v[108:111]
	v_mfma_f32_16x16x32_bf16 v[104:107], v[160:163], v[192:195], v[104:107]
	v_mfma_f32_16x16x32_bf16 v[92:95], v[144:147], v[200:203], v[92:95]
	v_mfma_f32_16x16x32_bf16 v[88:91], v[160:163], v[200:203], v[88:91]
	v_mfma_f32_16x16x32_bf16 v[76:79], v[144:147], v[208:211], v[76:79]
	v_mfma_f32_16x16x32_bf16 v[72:75], v[160:163], v[208:211], v[72:75]
	v_mfma_f32_16x16x32_bf16 v[124:127], v[156:159], v[188:191], v[124:127]
	v_mfma_f32_16x16x32_bf16 v[120:123], v[164:167], v[188:191], v[120:123]
	v_mfma_f32_16x16x32_bf16 v[108:111], v[156:159], v[196:199], v[108:111]
	v_mfma_f32_16x16x32_bf16 v[104:107], v[164:167], v[196:199], v[104:107]
	v_mfma_f32_16x16x32_bf16 v[92:95], v[156:159], v[204:207], v[92:95]
	v_mfma_f32_16x16x32_bf16 v[88:91], v[164:167], v[204:207], v[88:91]
	v_mfma_f32_16x16x32_bf16 v[76:79], v[156:159], v[212:215], v[76:79]
	v_mfma_f32_16x16x32_bf16 v[72:75], v[164:167], v[212:215], v[72:75]
	v_mfma_f32_16x16x32_bf16 v[116:119], v[168:171], v[184:187], v[116:119]
	v_mfma_f32_16x16x32_bf16 v[112:115], v[176:179], v[184:187], v[112:115]
	v_mfma_f32_16x16x32_bf16 v[100:103], v[168:171], v[192:195], v[100:103]
	v_mfma_f32_16x16x32_bf16 v[96:99], v[176:179], v[192:195], v[96:99]
	v_mfma_f32_16x16x32_bf16 v[84:87], v[168:171], v[200:203], v[84:87]
	v_mfma_f32_16x16x32_bf16 v[80:83], v[176:179], v[200:203], v[80:83]
	v_mfma_f32_16x16x32_bf16 v[68:71], v[168:171], v[208:211], v[68:71]
	v_mfma_f32_16x16x32_bf16 v[64:67], v[176:179], v[208:211], v[64:67]
	v_mfma_f32_16x16x32_bf16 v[116:119], v[172:175], v[188:191], v[116:119]
	v_mfma_f32_16x16x32_bf16 v[112:115], v[180:183], v[188:191], v[112:115]
	v_mfma_f32_16x16x32_bf16 v[100:103], v[172:175], v[196:199], v[100:103]
	v_mfma_f32_16x16x32_bf16 v[96:99], v[180:183], v[196:199], v[96:99]
	v_mfma_f32_16x16x32_bf16 v[84:87], v[172:175], v[204:207], v[84:87]
	v_mfma_f32_16x16x32_bf16 v[80:83], v[180:183], v[204:207], v[80:83]
	v_mfma_f32_16x16x32_bf16 v[68:71], v[172:175], v[212:215], v[68:71]
	v_mfma_f32_16x16x32_bf16 v[64:67], v[180:183], v[212:215], v[64:67]
	s_barrier
	s_add_u32 s100, s74, 0x80
	s_addc_u32 s101, s75, 0
	s_add_u32 s42, s74, 0x100080
	s_addc_u32 s43, s75, 0
	s_add_u32 s98, s30, 0x80
	s_addc_u32 s99, s31, 0
	s_add_i32 m0, s29, 0x18000
	s_nop 0
	global_load_lds_dwordx4 v130, s[100:101]
	s_add_i32 m0, s29, 0x1a000
	s_nop 0
	global_load_lds_dwordx4 v134, s[100:101]
	s_add_i32 m0, s29, 0x1c000
	s_nop 0
	global_load_lds_dwordx4 v130, s[42:43]
	s_add_i32 m0, s29, 0x1e000
	s_nop 0
	global_load_lds_dwordx4 v134, s[42:43]
	s_add_i32 m0, s29, 0x8000
	s_nop 0
	global_load_lds_dwordx4 v128, s[98:99]
	s_add_i32 m0, s29, 0xa000
	s_nop 0
	global_load_lds_dwordx4 v132, s[98:99]
	ds_read_b128 v[184:187], v155 offset:49152
	ds_read_b128 v[188:191], v155 offset:50176
	ds_read_b128 v[192:195], v155 offset:51200
	ds_read_b128 v[196:199], v155 offset:52224
	ds_read_b128 v[200:203], v155 offset:53248
	ds_read_b128 v[204:207], v155 offset:54272
	ds_read_b128 v[208:211], v155 offset:55296
	ds_read_b128 v[212:215], v155 offset:56320
	s_waitcnt vmcnt(8)
	s_waitcnt lgkmcnt(0)
	s_barrier
	v_mfma_f32_16x16x32_bf16 v[60:63], v[144:147], v[184:187], v[60:63]
	v_mfma_f32_16x16x32_bf16 v[56:59], v[160:163], v[184:187], v[56:59]
	v_mfma_f32_16x16x32_bf16 v[44:47], v[144:147], v[192:195], v[44:47]
	v_mfma_f32_16x16x32_bf16 v[40:43], v[160:163], v[192:195], v[40:43]
	v_mfma_f32_16x16x32_bf16 v[28:31], v[144:147], v[200:203], v[28:31]
	v_mfma_f32_16x16x32_bf16 v[24:27], v[160:163], v[200:203], v[24:27]
	v_mfma_f32_16x16x32_bf16 v[12:15], v[144:147], v[208:211], v[12:15]
	v_mfma_f32_16x16x32_bf16 v[8:11], v[160:163], v[208:211], v[8:11]
	v_mfma_f32_16x16x32_bf16 v[60:63], v[156:159], v[188:191], v[60:63]
	v_mfma_f32_16x16x32_bf16 v[56:59], v[164:167], v[188:191], v[56:59]
	v_mfma_f32_16x16x32_bf16 v[44:47], v[156:159], v[196:199], v[44:47]
	v_mfma_f32_16x16x32_bf16 v[40:43], v[164:167], v[196:199], v[40:43]
	v_mfma_f32_16x16x32_bf16 v[28:31], v[156:159], v[204:207], v[28:31]
	v_mfma_f32_16x16x32_bf16 v[24:27], v[164:167], v[204:207], v[24:27]
	v_mfma_f32_16x16x32_bf16 v[12:15], v[156:159], v[212:215], v[12:15]
	v_mfma_f32_16x16x32_bf16 v[8:11], v[164:167], v[212:215], v[8:11]
	v_mfma_f32_16x16x32_bf16 v[52:55], v[168:171], v[184:187], v[52:55]
	v_mfma_f32_16x16x32_bf16 v[48:51], v[176:179], v[184:187], v[48:51]
	v_mfma_f32_16x16x32_bf16 v[36:39], v[168:171], v[192:195], v[36:39]
	v_mfma_f32_16x16x32_bf16 v[32:35], v[176:179], v[192:195], v[32:35]
	v_mfma_f32_16x16x32_bf16 v[20:23], v[168:171], v[200:203], v[20:23]
	v_mfma_f32_16x16x32_bf16 v[16:19], v[176:179], v[200:203], v[16:19]
	v_mfma_f32_16x16x32_bf16 v[4:7], v[168:171], v[208:211], v[4:7]
	v_mfma_f32_16x16x32_bf16 v[0:3], v[176:179], v[208:211], v[0:3]
	v_mfma_f32_16x16x32_bf16 v[52:55], v[172:175], v[188:191], v[52:55]
	v_mfma_f32_16x16x32_bf16 v[48:51], v[180:183], v[188:191], v[48:51]
	v_mfma_f32_16x16x32_bf16 v[36:39], v[172:175], v[196:199], v[36:39]
	v_mfma_f32_16x16x32_bf16 v[32:35], v[180:183], v[196:199], v[32:35]
	v_mfma_f32_16x16x32_bf16 v[20:23], v[172:175], v[204:207], v[20:23]
	v_mfma_f32_16x16x32_bf16 v[16:19], v[180:183], v[204:207], v[16:19]
	v_mfma_f32_16x16x32_bf16 v[4:7], v[172:175], v[212:215], v[4:7]
	v_mfma_f32_16x16x32_bf16 v[0:3], v[180:183], v[212:215], v[0:3]
	s_barrier
	s_add_i32 s41, s41, 2
	s_add_u32 s72, s72, 0x100
	s_addc_u32 s73, s73, 0
	s_add_u32 s39, s39, 0x100
	s_addc_u32 s40, s40, 0
	s_cmp_gt_u32 s41, 61
	s_cbranch_scc0 .LBB0_182
	s_and_b64 vcc, exec, s[6:7]
	s_cbranch_vccz .LBB0_185
	s_barrier

.LBB0_401:
	s_add_i32 s38, s30, 2
	s_add_u32 s46, s44, 0x100
	s_addc_u32 s47, s45, 0
	s_cmp_eq_u32 s17, s30
	s_cselect_b32 s30, s34, s46
	s_cselect_b32 s31, s35, s47
	s_cselect_b32 s53, s41, s37
	s_cselect_b32 s52, s40, s36
	s_add_i32 m0, s60, 0xc000
	s_nop 0
	global_load_lds_dwordx4 v136, s[44:45]
	s_add_i32 m0, s60, 0xe000
	s_nop 0
	global_load_lds_dwordx4 v138, s[44:45]
	ds_read_b128 v[142:145], v169 offset:0
	ds_read_b128 v[146:149], v169 offset:1024
	ds_read_b128 v[150:153], v169 offset:2048
	ds_read_b128 v[154:157], v169 offset:3072
	ds_read_b128 v[158:161], v170 offset:0
	ds_read_b128 v[162:165], v170 offset:1024
	ds_read_b128 v[172:175], v170 offset:2048
	ds_read_b128 v[176:179], v170 offset:3072
	ds_read_b128 v[180:183], v171 offset:0
	ds_read_b128 v[184:187], v171 offset:1024
	ds_read_b128 v[188:191], v171 offset:2048
	ds_read_b128 v[192:195], v171 offset:3072
	ds_read_b128 v[196:199], v171 offset:4096
	ds_read_b128 v[200:203], v171 offset:5120
	ds_read_b128 v[204:207], v171 offset:6144
	ds_read_b128 v[208:211], v171 offset:7168
	s_waitcnt vmcnt(8)
	s_waitcnt lgkmcnt(0)
	s_barrier
	v_mfma_f32_16x16x32_bf16 v[124:127], v[142:145], v[180:183], v[124:127]
	v_mfma_f32_16x16x32_bf16 v[120:123], v[150:153], v[180:183], v[120:123]
	v_mfma_f32_16x16x32_bf16 v[108:111], v[142:145], v[188:191], v[108:111]
	v_mfma_f32_16x16x32_bf16 v[104:107], v[150:153], v[188:191], v[104:107]
	v_mfma_f32_16x16x32_bf16 v[92:95], v[142:145], v[196:199], v[92:95]
	v_mfma_f32_16x16x32_bf16 v[88:91], v[150:153], v[196:199], v[88:91]
	v_mfma_f32_16x16x32_bf16 v[76:79], v[142:145], v[204:207], v[76:79]
	v_mfma_f32_16x16x32_bf16 v[72:75], v[150:153], v[204:207], v[72:75]
	v_mfma_f32_16x16x32_bf16 v[124:127], v[146:149], v[184:187], v[124:127]
	v_mfma_f32_16x16x32_bf16 v[120:123], v[154:157], v[184:187], v[120:123]
	v_mfma_f32_16x16x32_bf16 v[108:111], v[146:149], v[192:195], v[108:111]
	v_mfma_f32_16x16x32_bf16 v[104:107], v[154:157], v[192:195], v[104:107]
	v_mfma_f32_16x16x32_bf16 v[92:95], v[146:149], v[200:203], v[92:95]
	v_mfma_f32_16x16x32_bf16 v[88:91], v[154:157], v[200:203], v[88:91]
	v_mfma_f32_16x16x32_bf16 v[76:79], v[146:149], v[208:211], v[76:79]
	v_mfma_f32_16x16x32_bf16 v[72:75], v[154:157], v[208:211], v[72:75]
	v_mfma_f32_16x16x32_bf16 v[116:119], v[158:161], v[180:183], v[116:119]
	v_mfma_f32_16x16x32_bf16 v[112:115], v[172:175], v[180:183], v[112:115]
	v_mfma_f32_16x16x32_bf16 v[100:103], v[158:161], v[188:191], v[100:103]
	v_mfma_f32_16x16x32_bf16 v[96:99], v[172:175], v[188:191], v[96:99]
	v_mfma_f32_16x16x32_bf16 v[84:87], v[158:161], v[196:199], v[84:87]
	v_mfma_f32_16x16x32_bf16 v[80:83], v[172:175], v[196:199], v[80:83]
	v_mfma_f32_16x16x32_bf16 v[68:71], v[158:161], v[204:207], v[68:71]
	v_mfma_f32_16x16x32_bf16 v[64:67], v[172:175], v[204:207], v[64:67]
	v_mfma_f32_16x16x32_bf16 v[116:119], v[162:165], v[184:187], v[116:119]
	v_mfma_f32_16x16x32_bf16 v[112:115], v[176:179], v[184:187], v[112:115]
	v_mfma_f32_16x16x32_bf16 v[100:103], v[162:165], v[192:195], v[100:103]
	v_mfma_f32_16x16x32_bf16 v[96:99], v[176:179], v[192:195], v[96:99]
	v_mfma_f32_16x16x32_bf16 v[84:87], v[162:165], v[200:203], v[84:87]
	v_mfma_f32_16x16x32_bf16 v[80:83], v[176:179], v[200:203], v[80:83]
	v_mfma_f32_16x16x32_bf16 v[68:71], v[162:165], v[208:211], v[68:71]
	v_mfma_f32_16x16x32_bf16 v[64:67], v[176:179], v[208:211], v[64:67]
	s_barrier
	s_add_u32 s42, s52, 0x2b0000
	s_addc_u32 s43, s53, 0
	s_add_i32 m0, s60, 0x10000
	s_nop 0
	global_load_lds_dwordx4 v130, s[52:53]
	s_add_i32 m0, s60, 0x12000
	s_nop 0
	global_load_lds_dwordx4 v134, s[52:53]
	s_add_i32 m0, s60, 0x14000
	s_nop 0
	global_load_lds_dwordx4 v130, s[42:43]
	s_add_i32 m0, s60, 0x16000
	s_nop 0
	global_load_lds_dwordx4 v134, s[42:43]
	s_add_i32 m0, s60, 0x0
	s_nop 0
	global_load_lds_dwordx4 v128, s[30:31]
	s_add_i32 m0, s60, 0x2000
	s_nop 0
	global_load_lds_dwordx4 v132, s[30:31]
	ds_read_b128 v[180:183], v171 offset:16384
	ds_read_b128 v[184:187], v171 offset:17408
	ds_read_b128 v[188:191], v171 offset:18432
	ds_read_b128 v[192:195], v171 offset:19456
	ds_read_b128 v[196:199], v171 offset:20480
	ds_read_b128 v[200:203], v171 offset:21504
	ds_read_b128 v[204:207], v171 offset:22528
	ds_read_b128 v[208:211], v171 offset:23552
	s_waitcnt vmcnt(8)
	s_waitcnt lgkmcnt(0)
	s_barrier
	v_mfma_f32_16x16x32_bf16 v[60:63], v[142:145], v[180:183], v[60:63]
	v_mfma_f32_16x16x32_bf16 v[56:59], v[150:153], v[180:183], v[56:59]
	v_mfma_f32_16x16x32_bf16 v[44:47], v[142:145], v[188:191], v[44:47]
	v_mfma_f32_16x16x32_bf16 v[40:43], v[150:153], v[188:191], v[40:43]
	v_mfma_f32_16x16x32_bf16 v[28:31], v[142:145], v[196:199], v[28:31]
	v_mfma_f32_16x16x32_bf16 v[24:27], v[150:153], v[196:199], v[24:27]
	v_mfma_f32_16x16x32_bf16 v[12:15], v[142:145], v[204:207], v[12:15]
	v_mfma_f32_16x16x32_bf16 v[8:11], v[150:153], v[204:207], v[8:11]
	v_mfma_f32_16x16x32_bf16 v[60:63], v[146:149], v[184:187], v[60:63]
	v_mfma_f32_16x16x32_bf16 v[56:59], v[154:157], v[184:187], v[56:59]
	v_mfma_f32_16x16x32_bf16 v[44:47], v[146:149], v[192:195], v[44:47]
	v_mfma_f32_16x16x32_bf16 v[40:43], v[154:157], v[192:195], v[40:43]
	v_mfma_f32_16x16x32_bf16 v[28:31], v[146:149], v[200:203], v[28:31]
	v_mfma_f32_16x16x32_bf16 v[24:27], v[154:157], v[200:203], v[24:27]
	v_mfma_f32_16x16x32_bf16 v[12:15], v[146:149], v[208:211], v[12:15]
	v_mfma_f32_16x16x32_bf16 v[8:11], v[154:157], v[208:211], v[8:11]
	v_mfma_f32_16x16x32_bf16 v[52:55], v[158:161], v[180:183], v[52:55]
	v_mfma_f32_16x16x32_bf16 v[48:51], v[172:175], v[180:183], v[48:51]
	v_mfma_f32_16x16x32_bf16 v[36:39], v[158:161], v[188:191], v[36:39]
	v_mfma_f32_16x16x32_bf16 v[32:35], v[172:175], v[188:191], v[32:35]
	v_mfma_f32_16x16x32_bf16 v[20:23], v[158:161], v[196:199], v[20:23]
	v_mfma_f32_16x16x32_bf16 v[16:19], v[172:175], v[196:199], v[16:19]
	v_mfma_f32_16x16x32_bf16 v[4:7], v[158:161], v[204:207], v[4:7]
	v_mfma_f32_16x16x32_bf16 v[0:3], v[172:175], v[204:207], v[0:3]
	v_mfma_f32_16x16x32_bf16 v[52:55], v[162:165], v[184:187], v[52:55]
	v_mfma_f32_16x16x32_bf16 v[48:51], v[176:179], v[184:187], v[48:51]
	v_mfma_f32_16x16x32_bf16 v[36:39], v[162:165], v[192:195], v[36:39]
	v_mfma_f32_16x16x32_bf16 v[32:35], v[176:179], v[192:195], v[32:35]
	v_mfma_f32_16x16x32_bf16 v[20:23], v[162:165], v[200:203], v[20:23]
	v_mfma_f32_16x16x32_bf16 v[16:19], v[176:179], v[200:203], v[16:19]
	v_mfma_f32_16x16x32_bf16 v[4:7], v[162:165], v[208:211], v[4:7]
	v_mfma_f32_16x16x32_bf16 v[0:3], v[176:179], v[208:211], v[0:3]
	s_barrier
	s_add_u32 s98, s30, 0x2b0000
	s_addc_u32 s99, s31, 0
	s_add_i32 m0, s60, 0x4000
	s_nop 0
	global_load_lds_dwordx4 v128, s[98:99]
	s_add_i32 m0, s60, 0x6000
	s_nop 0
	global_load_lds_dwordx4 v132, s[98:99]
	ds_read_b128 v[142:145], v169 offset:32768
	ds_read_b128 v[146:149], v169 offset:33792
	ds_read_b128 v[150:153], v169 offset:34816
	ds_read_b128 v[154:157], v169 offset:35840
	ds_read_b128 v[158:161], v170 offset:32768
	ds_read_b128 v[162:165], v170 offset:33792
	ds_read_b128 v[172:175], v170 offset:34816
	ds_read_b128 v[176:179], v170 offset:35840
	ds_read_b128 v[180:183], v171 offset:32768
	ds_read_b128 v[184:187], v171 offset:33792
	ds_read_b128 v[188:191], v171 offset:34816
	ds_read_b128 v[192:195], v171 offset:35840
	ds_read_b128 v[196:199], v171 offset:36864
	ds_read_b128 v[200:203], v171 offset:37888
	ds_read_b128 v[204:207], v171 offset:38912
	ds_read_b128 v[208:211], v171 offset:39936
	s_waitcnt vmcnt(8)
	s_waitcnt lgkmcnt(0)
	s_barrier
	v_mfma_f32_16x16x32_bf16 v[124:127], v[142:145], v[180:183], v[124:127]
	v_mfma_f32_16x16x32_bf16 v[120:123], v[150:153], v[180:183], v[120:123]
	v_mfma_f32_16x16x32_bf16 v[108:111], v[142:145], v[188:191], v[108:111]
	v_mfma_f32_16x16x32_bf16 v[104:107], v[150:153], v[188:191], v[104:107]
	v_mfma_f32_16x16x32_bf16 v[92:95], v[142:145], v[196:199], v[92:95]
	v_mfma_f32_16x16x32_bf16 v[88:91], v[150:153], v[196:199], v[88:91]
	v_mfma_f32_16x16x32_bf16 v[76:79], v[142:145], v[204:207], v[76:79]
	v_mfma_f32_16x16x32_bf16 v[72:75], v[150:153], v[204:207], v[72:75]
	v_mfma_f32_16x16x32_bf16 v[124:127], v[146:149], v[184:187], v[124:127]
	v_mfma_f32_16x16x32_bf16 v[120:123], v[154:157], v[184:187], v[120:123]
	v_mfma_f32_16x16x32_bf16 v[108:111], v[146:149], v[192:195], v[108:111]
	v_mfma_f32_16x16x32_bf16 v[104:107], v[154:157], v[192:195], v[104:107]
	v_mfma_f32_16x16x32_bf16 v[92:95], v[146:149], v[200:203], v[92:95]
	v_mfma_f32_16x16x32_bf16 v[88:91], v[154:157], v[200:203], v[88:91]
	v_mfma_f32_16x16x32_bf16 v[76:79], v[146:149], v[208:211], v[76:79]
	v_mfma_f32_16x16x32_bf16 v[72:75], v[154:157], v[208:211], v[72:75]
	v_mfma_f32_16x16x32_bf16 v[116:119], v[158:161], v[180:183], v[116:119]
	v_mfma_f32_16x16x32_bf16 v[112:115], v[172:175], v[180:183], v[112:115]
	v_mfma_f32_16x16x32_bf16 v[100:103], v[158:161], v[188:191], v[100:103]
	v_mfma_f32_16x16x32_bf16 v[96:99], v[172:175], v[188:191], v[96:99]
	v_mfma_f32_16x16x32_bf16 v[84:87], v[158:161], v[196:199], v[84:87]
	v_mfma_f32_16x16x32_bf16 v[80:83], v[172:175], v[196:199], v[80:83]
	v_mfma_f32_16x16x32_bf16 v[68:71], v[158:161], v[204:207], v[68:71]
	v_mfma_f32_16x16x32_bf16 v[64:67], v[172:175], v[204:207], v[64:67]
	v_mfma_f32_16x16x32_bf16 v[116:119], v[162:165], v[184:187], v[116:119]
	v_mfma_f32_16x16x32_bf16 v[112:115], v[176:179], v[184:187], v[112:115]
	v_mfma_f32_16x16x32_bf16 v[100:103], v[162:165], v[192:195], v[100:103]
	v_mfma_f32_16x16x32_bf16 v[96:99], v[176:179], v[192:195], v[96:99]
	v_mfma_f32_16x16x32_bf16 v[84:87], v[162:165], v[200:203], v[84:87]
	v_mfma_f32_16x16x32_bf16 v[80:83], v[176:179], v[200:203], v[80:83]
	v_mfma_f32_16x16x32_bf16 v[68:71], v[162:165], v[208:211], v[68:71]
	v_mfma_f32_16x16x32_bf16 v[64:67], v[176:179], v[208:211], v[64:67]
	s_barrier
	s_add_u32 s100, s52, 0x80
	s_addc_u32 s101, s53, 0
	s_add_u32 s42, s52, 0x2b0080
	s_addc_u32 s43, s53, 0
	s_add_u32 s98, s30, 0x80
	s_addc_u32 s99, s31, 0
	s_add_i32 m0, s60, 0x18000
	s_nop 0
	global_load_lds_dwordx4 v130, s[100:101]
	s_add_i32 m0, s60, 0x1a000
	s_nop 0
	global_load_lds_dwordx4 v134, s[100:101]
	s_add_i32 m0, s60, 0x1c000
	s_nop 0
	global_load_lds_dwordx4 v130, s[42:43]
	s_add_i32 m0, s60, 0x1e000
	s_nop 0
	global_load_lds_dwordx4 v134, s[42:43]
	s_add_i32 m0, s60, 0x8000
	s_nop 0
	global_load_lds_dwordx4 v128, s[98:99]
	s_add_i32 m0, s60, 0xa000
	s_nop 0
	global_load_lds_dwordx4 v132, s[98:99]
	ds_read_b128 v[180:183], v171 offset:49152
	ds_read_b128 v[184:187], v171 offset:50176
	ds_read_b128 v[188:191], v171 offset:51200
	ds_read_b128 v[192:195], v171 offset:52224
	ds_read_b128 v[196:199], v171 offset:53248
	ds_read_b128 v[200:203], v171 offset:54272
	ds_read_b128 v[204:207], v171 offset:55296
	ds_read_b128 v[208:211], v171 offset:56320
	s_waitcnt vmcnt(8)
	s_waitcnt lgkmcnt(0)
	s_barrier
	v_mfma_f32_16x16x32_bf16 v[60:63], v[142:145], v[180:183], v[60:63]
	v_mfma_f32_16x16x32_bf16 v[56:59], v[150:153], v[180:183], v[56:59]
	v_mfma_f32_16x16x32_bf16 v[44:47], v[142:145], v[188:191], v[44:47]
	v_mfma_f32_16x16x32_bf16 v[40:43], v[150:153], v[188:191], v[40:43]
	v_mfma_f32_16x16x32_bf16 v[28:31], v[142:145], v[196:199], v[28:31]
	v_mfma_f32_16x16x32_bf16 v[24:27], v[150:153], v[196:199], v[24:27]
	v_mfma_f32_16x16x32_bf16 v[12:15], v[142:145], v[204:207], v[12:15]
	v_mfma_f32_16x16x32_bf16 v[8:11], v[150:153], v[204:207], v[8:11]
	v_mfma_f32_16x16x32_bf16 v[60:63], v[146:149], v[184:187], v[60:63]
	v_mfma_f32_16x16x32_bf16 v[56:59], v[154:157], v[184:187], v[56:59]
	v_mfma_f32_16x16x32_bf16 v[44:47], v[146:149], v[192:195], v[44:47]
	v_mfma_f32_16x16x32_bf16 v[40:43], v[154:157], v[192:195], v[40:43]
	v_mfma_f32_16x16x32_bf16 v[28:31], v[146:149], v[200:203], v[28:31]
	v_mfma_f32_16x16x32_bf16 v[24:27], v[154:157], v[200:203], v[24:27]
	v_mfma_f32_16x16x32_bf16 v[12:15], v[146:149], v[208:211], v[12:15]
	v_mfma_f32_16x16x32_bf16 v[8:11], v[154:157], v[208:211], v[8:11]
	v_mfma_f32_16x16x32_bf16 v[52:55], v[158:161], v[180:183], v[52:55]
	v_mfma_f32_16x16x32_bf16 v[48:51], v[172:175], v[180:183], v[48:51]
	v_mfma_f32_16x16x32_bf16 v[36:39], v[158:161], v[188:191], v[36:39]
	v_mfma_f32_16x16x32_bf16 v[32:35], v[172:175], v[188:191], v[32:35]
	v_mfma_f32_16x16x32_bf16 v[20:23], v[158:161], v[196:199], v[20:23]
	v_mfma_f32_16x16x32_bf16 v[16:19], v[172:175], v[196:199], v[16:19]
	v_mfma_f32_16x16x32_bf16 v[4:7], v[158:161], v[204:207], v[4:7]
	v_mfma_f32_16x16x32_bf16 v[0:3], v[172:175], v[204:207], v[0:3]
	v_mfma_f32_16x16x32_bf16 v[52:55], v[162:165], v[184:187], v[52:55]
	v_mfma_f32_16x16x32_bf16 v[48:51], v[176:179], v[184:187], v[48:51]
	v_mfma_f32_16x16x32_bf16 v[36:39], v[162:165], v[192:195], v[36:39]
	v_mfma_f32_16x16x32_bf16 v[32:35], v[176:179], v[192:195], v[32:35]
	v_mfma_f32_16x16x32_bf16 v[20:23], v[162:165], v[200:203], v[20:23]
	v_mfma_f32_16x16x32_bf16 v[16:19], v[176:179], v[200:203], v[16:19]
	v_mfma_f32_16x16x32_bf16 v[4:7], v[162:165], v[208:211], v[4:7]
	v_mfma_f32_16x16x32_bf16 v[0:3], v[176:179], v[208:211], v[0:3]
	s_barrier
	s_add_u32 s36, s36, 0x100
	s_addc_u32 s37, s37, 0
	s_cmp_ge_i32 s38, s87
	s_mov_b64 s[44:45], s[46:47]
	s_mov_b32 s30, s38
	s_cbranch_scc0 .LBB0_401
	s_and_b64 vcc, exec, s[12:13]
	s_cbranch_vccz .LBB0_404

.LBB0_1299:
	s_add_u32 s36, s34, 0xfff00080
	s_addc_u32 s37, s35, -1
	s_cmp_eq_u32 s57, 60
	s_cselect_b32 s39, s13, s37
	s_cselect_b32 s38, s53, s36
	s_cselect_b32 s37, s11, s56
	s_cselect_b32 s36, s54, s55
	s_add_i32 m0, s31, 0xc000
	s_nop 0
	global_load_lds_dwordx4 v136, s[34:35]
	s_add_i32 m0, s31, 0xe000
	s_nop 0
	global_load_lds_dwordx4 v138, s[34:35]
	ds_read_b128 v[144:147], v153 offset:0
	ds_read_b128 v[156:159], v153 offset:1024
	ds_read_b128 v[160:163], v153 offset:2048
	ds_read_b128 v[164:167], v153 offset:3072
	ds_read_b128 v[168:171], v154 offset:0
	ds_read_b128 v[172:175], v154 offset:1024
	ds_read_b128 v[176:179], v154 offset:2048
	ds_read_b128 v[180:183], v154 offset:3072
	ds_read_b128 v[184:187], v155 offset:0
	ds_read_b128 v[188:191], v155 offset:1024
	ds_read_b128 v[192:195], v155 offset:2048
	ds_read_b128 v[196:199], v155 offset:3072
	ds_read_b128 v[202:205], v155 offset:4096
	ds_read_b128 v[206:209], v155 offset:5120
	ds_read_b128 v[210:213], v155 offset:6144
	ds_read_b128 v[214:217], v155 offset:7168
	s_waitcnt vmcnt(8)
	s_waitcnt lgkmcnt(0)
	s_barrier
	v_mfma_f32_16x16x32_bf16 v[124:127], v[144:147], v[184:187], v[124:127]
	v_mfma_f32_16x16x32_bf16 v[120:123], v[160:163], v[184:187], v[120:123]
	v_mfma_f32_16x16x32_bf16 v[108:111], v[144:147], v[192:195], v[108:111]
	v_mfma_f32_16x16x32_bf16 v[104:107], v[160:163], v[192:195], v[104:107]
	v_mfma_f32_16x16x32_bf16 v[92:95], v[144:147], v[202:205], v[92:95]
	v_mfma_f32_16x16x32_bf16 v[88:91], v[160:163], v[202:205], v[88:91]
	v_mfma_f32_16x16x32_bf16 v[76:79], v[144:147], v[210:213], v[76:79]
	v_mfma_f32_16x16x32_bf16 v[72:75], v[160:163], v[210:213], v[72:75]
	v_mfma_f32_16x16x32_bf16 v[124:127], v[156:159], v[188:191], v[124:127]
	v_mfma_f32_16x16x32_bf16 v[120:123], v[164:167], v[188:191], v[120:123]
	v_mfma_f32_16x16x32_bf16 v[108:111], v[156:159], v[196:199], v[108:111]
	v_mfma_f32_16x16x32_bf16 v[104:107], v[164:167], v[196:199], v[104:107]
	v_mfma_f32_16x16x32_bf16 v[92:95], v[156:159], v[206:209], v[92:95]
	v_mfma_f32_16x16x32_bf16 v[88:91], v[164:167], v[206:209], v[88:91]
	v_mfma_f32_16x16x32_bf16 v[76:79], v[156:159], v[214:217], v[76:79]
	v_mfma_f32_16x16x32_bf16 v[72:75], v[164:167], v[214:217], v[72:75]
	v_mfma_f32_16x16x32_bf16 v[116:119], v[168:171], v[184:187], v[116:119]
	v_mfma_f32_16x16x32_bf16 v[112:115], v[176:179], v[184:187], v[112:115]
	v_mfma_f32_16x16x32_bf16 v[100:103], v[168:171], v[192:195], v[100:103]
	v_mfma_f32_16x16x32_bf16 v[96:99], v[176:179], v[192:195], v[96:99]
	v_mfma_f32_16x16x32_bf16 v[84:87], v[168:171], v[202:205], v[84:87]
	v_mfma_f32_16x16x32_bf16 v[80:83], v[176:179], v[202:205], v[80:83]
	v_mfma_f32_16x16x32_bf16 v[68:71], v[168:171], v[210:213], v[68:71]
	v_mfma_f32_16x16x32_bf16 v[64:67], v[176:179], v[210:213], v[64:67]
	v_mfma_f32_16x16x32_bf16 v[116:119], v[172:175], v[188:191], v[116:119]
	v_mfma_f32_16x16x32_bf16 v[112:115], v[180:183], v[188:191], v[112:115]
	v_mfma_f32_16x16x32_bf16 v[100:103], v[172:175], v[196:199], v[100:103]
	v_mfma_f32_16x16x32_bf16 v[96:99], v[180:183], v[196:199], v[96:99]
	v_mfma_f32_16x16x32_bf16 v[84:87], v[172:175], v[206:209], v[84:87]
	v_mfma_f32_16x16x32_bf16 v[80:83], v[180:183], v[206:209], v[80:83]
	v_mfma_f32_16x16x32_bf16 v[68:71], v[172:175], v[214:217], v[68:71]
	v_mfma_f32_16x16x32_bf16 v[64:67], v[180:183], v[214:217], v[64:67]
	s_barrier
	s_add_u32 s58, s36, 0x100000
	s_addc_u32 s59, s37, 0
	s_add_i32 m0, s31, 0x10000
	s_nop 0
	global_load_lds_dwordx4 v130, s[36:37]
	s_add_i32 m0, s31, 0x12000
	s_nop 0
	global_load_lds_dwordx4 v134, s[36:37]
	s_add_i32 m0, s31, 0x14000
	s_nop 0
	global_load_lds_dwordx4 v130, s[58:59]
	s_add_i32 m0, s31, 0x16000
	s_nop 0
	global_load_lds_dwordx4 v134, s[58:59]
	s_add_i32 m0, s31, 0x0
	s_nop 0
	global_load_lds_dwordx4 v128, s[38:39]
	s_add_i32 m0, s31, 0x2000
	s_nop 0
	global_load_lds_dwordx4 v132, s[38:39]
	ds_read_b128 v[184:187], v155 offset:16384
	ds_read_b128 v[188:191], v155 offset:17408
	ds_read_b128 v[192:195], v155 offset:18432
	ds_read_b128 v[196:199], v155 offset:19456
	ds_read_b128 v[202:205], v155 offset:20480
	ds_read_b128 v[206:209], v155 offset:21504
	ds_read_b128 v[210:213], v155 offset:22528
	ds_read_b128 v[214:217], v155 offset:23552
	s_waitcnt vmcnt(8)
	s_waitcnt lgkmcnt(0)
	s_barrier
	v_mfma_f32_16x16x32_bf16 v[60:63], v[144:147], v[184:187], v[60:63]
	v_mfma_f32_16x16x32_bf16 v[56:59], v[160:163], v[184:187], v[56:59]
	v_mfma_f32_16x16x32_bf16 v[44:47], v[144:147], v[192:195], v[44:47]
	v_mfma_f32_16x16x32_bf16 v[40:43], v[160:163], v[192:195], v[40:43]
	v_mfma_f32_16x16x32_bf16 v[28:31], v[144:147], v[202:205], v[28:31]
	v_mfma_f32_16x16x32_bf16 v[24:27], v[160:163], v[202:205], v[24:27]
	v_mfma_f32_16x16x32_bf16 v[12:15], v[144:147], v[210:213], v[12:15]
	v_mfma_f32_16x16x32_bf16 v[8:11], v[160:163], v[210:213], v[8:11]
	v_mfma_f32_16x16x32_bf16 v[60:63], v[156:159], v[188:191], v[60:63]
	v_mfma_f32_16x16x32_bf16 v[56:59], v[164:167], v[188:191], v[56:59]
	v_mfma_f32_16x16x32_bf16 v[44:47], v[156:159], v[196:199], v[44:47]
	v_mfma_f32_16x16x32_bf16 v[40:43], v[164:167], v[196:199], v[40:43]
	v_mfma_f32_16x16x32_bf16 v[28:31], v[156:159], v[206:209], v[28:31]
	v_mfma_f32_16x16x32_bf16 v[24:27], v[164:167], v[206:209], v[24:27]
	v_mfma_f32_16x16x32_bf16 v[12:15], v[156:159], v[214:217], v[12:15]
	v_mfma_f32_16x16x32_bf16 v[8:11], v[164:167], v[214:217], v[8:11]
	v_mfma_f32_16x16x32_bf16 v[52:55], v[168:171], v[184:187], v[52:55]
	v_mfma_f32_16x16x32_bf16 v[48:51], v[176:179], v[184:187], v[48:51]
	v_mfma_f32_16x16x32_bf16 v[36:39], v[168:171], v[192:195], v[36:39]
	v_mfma_f32_16x16x32_bf16 v[32:35], v[176:179], v[192:195], v[32:35]
	v_mfma_f32_16x16x32_bf16 v[20:23], v[168:171], v[202:205], v[20:23]
	v_mfma_f32_16x16x32_bf16 v[16:19], v[176:179], v[202:205], v[16:19]
	v_mfma_f32_16x16x32_bf16 v[4:7], v[168:171], v[210:213], v[4:7]
	v_mfma_f32_16x16x32_bf16 v[0:3], v[176:179], v[210:213], v[0:3]
	v_mfma_f32_16x16x32_bf16 v[52:55], v[172:175], v[188:191], v[52:55]
	v_mfma_f32_16x16x32_bf16 v[48:51], v[180:183], v[188:191], v[48:51]
	v_mfma_f32_16x16x32_bf16 v[36:39], v[172:175], v[196:199], v[36:39]
	v_mfma_f32_16x16x32_bf16 v[32:35], v[180:183], v[196:199], v[32:35]
	v_mfma_f32_16x16x32_bf16 v[20:23], v[172:175], v[206:209], v[20:23]
	v_mfma_f32_16x16x32_bf16 v[16:19], v[180:183], v[206:209], v[16:19]
	v_mfma_f32_16x16x32_bf16 v[4:7], v[172:175], v[214:217], v[4:7]
	v_mfma_f32_16x16x32_bf16 v[0:3], v[180:183], v[214:217], v[0:3]
	s_barrier
	s_add_u32 s98, s38, 0x100000
	s_addc_u32 s99, s39, 0
	s_add_i32 m0, s31, 0x4000
	s_nop 0
	global_load_lds_dwordx4 v128, s[98:99]
	s_add_i32 m0, s31, 0x6000
	s_nop 0
	global_load_lds_dwordx4 v132, s[98:99]
	ds_read_b128 v[144:147], v153 offset:32768
	ds_read_b128 v[156:159], v153 offset:33792
	ds_read_b128 v[160:163], v153 offset:34816
	ds_read_b128 v[164:167], v153 offset:35840
	ds_read_b128 v[168:171], v154 offset:32768
	ds_read_b128 v[172:175], v154 offset:33792
	ds_read_b128 v[176:179], v154 offset:34816
	ds_read_b128 v[180:183], v154 offset:35840
	ds_read_b128 v[184:187], v155 offset:32768
	ds_read_b128 v[188:191], v155 offset:33792
	ds_read_b128 v[192:195], v155 offset:34816
	ds_read_b128 v[196:199], v155 offset:35840
	ds_read_b128 v[202:205], v155 offset:36864
	ds_read_b128 v[206:209], v155 offset:37888
	ds_read_b128 v[210:213], v155 offset:38912
	ds_read_b128 v[214:217], v155 offset:39936
	s_waitcnt vmcnt(8)
	s_waitcnt lgkmcnt(0)
	s_barrier
	v_mfma_f32_16x16x32_bf16 v[124:127], v[144:147], v[184:187], v[124:127]
	v_mfma_f32_16x16x32_bf16 v[120:123], v[160:163], v[184:187], v[120:123]
	v_mfma_f32_16x16x32_bf16 v[108:111], v[144:147], v[192:195], v[108:111]
	v_mfma_f32_16x16x32_bf16 v[104:107], v[160:163], v[192:195], v[104:107]
	v_mfma_f32_16x16x32_bf16 v[92:95], v[144:147], v[202:205], v[92:95]
	v_mfma_f32_16x16x32_bf16 v[88:91], v[160:163], v[202:205], v[88:91]
	v_mfma_f32_16x16x32_bf16 v[76:79], v[144:147], v[210:213], v[76:79]
	v_mfma_f32_16x16x32_bf16 v[72:75], v[160:163], v[210:213], v[72:75]
	v_mfma_f32_16x16x32_bf16 v[124:127], v[156:159], v[188:191], v[124:127]
	v_mfma_f32_16x16x32_bf16 v[120:123], v[164:167], v[188:191], v[120:123]
	v_mfma_f32_16x16x32_bf16 v[108:111], v[156:159], v[196:199], v[108:111]
	v_mfma_f32_16x16x32_bf16 v[104:107], v[164:167], v[196:199], v[104:107]
	v_mfma_f32_16x16x32_bf16 v[92:95], v[156:159], v[206:209], v[92:95]
	v_mfma_f32_16x16x32_bf16 v[88:91], v[164:167], v[206:209], v[88:91]
	v_mfma_f32_16x16x32_bf16 v[76:79], v[156:159], v[214:217], v[76:79]
	v_mfma_f32_16x16x32_bf16 v[72:75], v[164:167], v[214:217], v[72:75]
	v_mfma_f32_16x16x32_bf16 v[116:119], v[168:171], v[184:187], v[116:119]
	v_mfma_f32_16x16x32_bf16 v[112:115], v[176:179], v[184:187], v[112:115]
	v_mfma_f32_16x16x32_bf16 v[100:103], v[168:171], v[192:195], v[100:103]
	v_mfma_f32_16x16x32_bf16 v[96:99], v[176:179], v[192:195], v[96:99]
	v_mfma_f32_16x16x32_bf16 v[84:87], v[168:171], v[202:205], v[84:87]
	v_mfma_f32_16x16x32_bf16 v[80:83], v[176:179], v[202:205], v[80:83]
	v_mfma_f32_16x16x32_bf16 v[68:71], v[168:171], v[210:213], v[68:71]
	v_mfma_f32_16x16x32_bf16 v[64:67], v[176:179], v[210:213], v[64:67]
	v_mfma_f32_16x16x32_bf16 v[116:119], v[172:175], v[188:191], v[116:119]
	v_mfma_f32_16x16x32_bf16 v[112:115], v[180:183], v[188:191], v[112:115]
	v_mfma_f32_16x16x32_bf16 v[100:103], v[172:175], v[196:199], v[100:103]
	v_mfma_f32_16x16x32_bf16 v[96:99], v[180:183], v[196:199], v[96:99]
	v_mfma_f32_16x16x32_bf16 v[84:87], v[172:175], v[206:209], v[84:87]
	v_mfma_f32_16x16x32_bf16 v[80:83], v[180:183], v[206:209], v[80:83]
	v_mfma_f32_16x16x32_bf16 v[68:71], v[172:175], v[214:217], v[68:71]
	v_mfma_f32_16x16x32_bf16 v[64:67], v[180:183], v[214:217], v[64:67]
	s_barrier
	s_add_u32 s100, s36, 0x80
	s_addc_u32 s101, s37, 0
	s_add_u32 s58, s36, 0x100080
	s_addc_u32 s59, s37, 0
	s_add_u32 s98, s38, 0x80
	s_addc_u32 s99, s39, 0
	s_add_i32 m0, s31, 0x18000
	s_nop 0
	global_load_lds_dwordx4 v130, s[100:101]
	s_add_i32 m0, s31, 0x1a000
	s_nop 0
	global_load_lds_dwordx4 v134, s[100:101]
	s_add_i32 m0, s31, 0x1c000
	s_nop 0
	global_load_lds_dwordx4 v130, s[58:59]
	s_add_i32 m0, s31, 0x1e000
	s_nop 0
	global_load_lds_dwordx4 v134, s[58:59]
	s_add_i32 m0, s31, 0x8000
	s_nop 0
	global_load_lds_dwordx4 v128, s[98:99]
	s_add_i32 m0, s31, 0xa000
	s_nop 0
	global_load_lds_dwordx4 v132, s[98:99]
	ds_read_b128 v[184:187], v155 offset:49152
	ds_read_b128 v[188:191], v155 offset:50176
	ds_read_b128 v[192:195], v155 offset:51200
	ds_read_b128 v[196:199], v155 offset:52224
	ds_read_b128 v[202:205], v155 offset:53248
	ds_read_b128 v[206:209], v155 offset:54272
	ds_read_b128 v[210:213], v155 offset:55296
	ds_read_b128 v[214:217], v155 offset:56320
	s_waitcnt vmcnt(8)
	s_waitcnt lgkmcnt(0)
	s_barrier
	v_mfma_f32_16x16x32_bf16 v[60:63], v[144:147], v[184:187], v[60:63]
	v_mfma_f32_16x16x32_bf16 v[56:59], v[160:163], v[184:187], v[56:59]
	v_mfma_f32_16x16x32_bf16 v[44:47], v[144:147], v[192:195], v[44:47]
	v_mfma_f32_16x16x32_bf16 v[40:43], v[160:163], v[192:195], v[40:43]
	v_mfma_f32_16x16x32_bf16 v[28:31], v[144:147], v[202:205], v[28:31]
	v_mfma_f32_16x16x32_bf16 v[24:27], v[160:163], v[202:205], v[24:27]
	v_mfma_f32_16x16x32_bf16 v[12:15], v[144:147], v[210:213], v[12:15]
	v_mfma_f32_16x16x32_bf16 v[8:11], v[160:163], v[210:213], v[8:11]
	v_mfma_f32_16x16x32_bf16 v[60:63], v[156:159], v[188:191], v[60:63]
	v_mfma_f32_16x16x32_bf16 v[56:59], v[164:167], v[188:191], v[56:59]
	v_mfma_f32_16x16x32_bf16 v[44:47], v[156:159], v[196:199], v[44:47]
	v_mfma_f32_16x16x32_bf16 v[40:43], v[164:167], v[196:199], v[40:43]
	v_mfma_f32_16x16x32_bf16 v[28:31], v[156:159], v[206:209], v[28:31]
	v_mfma_f32_16x16x32_bf16 v[24:27], v[164:167], v[206:209], v[24:27]
	v_mfma_f32_16x16x32_bf16 v[12:15], v[156:159], v[214:217], v[12:15]
	v_mfma_f32_16x16x32_bf16 v[8:11], v[164:167], v[214:217], v[8:11]
	v_mfma_f32_16x16x32_bf16 v[52:55], v[168:171], v[184:187], v[52:55]
	v_mfma_f32_16x16x32_bf16 v[48:51], v[176:179], v[184:187], v[48:51]
	v_mfma_f32_16x16x32_bf16 v[36:39], v[168:171], v[192:195], v[36:39]
	v_mfma_f32_16x16x32_bf16 v[32:35], v[176:179], v[192:195], v[32:35]
	v_mfma_f32_16x16x32_bf16 v[20:23], v[168:171], v[202:205], v[20:23]
	v_mfma_f32_16x16x32_bf16 v[16:19], v[176:179], v[202:205], v[16:19]
	v_mfma_f32_16x16x32_bf16 v[4:7], v[168:171], v[210:213], v[4:7]
	v_mfma_f32_16x16x32_bf16 v[0:3], v[176:179], v[210:213], v[0:3]
	v_mfma_f32_16x16x32_bf16 v[52:55], v[172:175], v[188:191], v[52:55]
	v_mfma_f32_16x16x32_bf16 v[48:51], v[180:183], v[188:191], v[48:51]
	v_mfma_f32_16x16x32_bf16 v[36:39], v[172:175], v[196:199], v[36:39]
	v_mfma_f32_16x16x32_bf16 v[32:35], v[180:183], v[196:199], v[32:35]
	v_mfma_f32_16x16x32_bf16 v[20:23], v[172:175], v[206:209], v[20:23]
	v_mfma_f32_16x16x32_bf16 v[16:19], v[180:183], v[206:209], v[16:19]
	v_mfma_f32_16x16x32_bf16 v[4:7], v[172:175], v[214:217], v[4:7]
	v_mfma_f32_16x16x32_bf16 v[0:3], v[180:183], v[214:217], v[0:3]
	s_barrier
	s_add_i32 s57, s57, 2
	s_add_u32 s34, s34, 0x100
	s_addc_u32 s35, s35, 0
	s_add_u32 s55, s55, 0x100
	s_addc_u32 s56, s56, 0
	s_cmp_gt_u32 s57, 61
	s_cbranch_scc0 .LBB0_1299
	s_and_b64 vcc, exec, s[6:7]
	s_cbranch_vccz .LBB0_1302
	s_barrier

.LBB0_1409:
	s_add_i32 s70, s46, 2
	s_add_u32 s44, s42, 0x100
	s_addc_u32 s45, s43, 0
	s_cmp_eq_u32 s37, s46
	s_cselect_b32 s46, s40, s68
	s_cselect_b32 s49, s39, s45
	s_cselect_b32 s48, s38, s44
	s_cselect_b32 s47, s41, s69
	s_add_i32 m0, s50, 0xc000
	s_nop 0
	global_load_lds_dwordx4 v140, s[42:43]
	s_add_i32 m0, s50, 0xe000
	s_nop 0
	global_load_lds_dwordx4 v142, s[42:43]
	ds_read_b128 v[128:131], v177 offset:0
	ds_read_b128 v[146:149], v177 offset:1024
	ds_read_b128 v[150:153], v177 offset:2048
	ds_read_b128 v[154:157], v177 offset:3072
	ds_read_b128 v[158:161], v178 offset:0
	ds_read_b128 v[162:165], v178 offset:1024
	ds_read_b128 v[166:169], v178 offset:2048
	ds_read_b128 v[170:173], v178 offset:3072
	ds_read_b128 v[180:183], v179 offset:0
	ds_read_b128 v[184:187], v179 offset:1024
	ds_read_b128 v[188:191], v179 offset:2048
	ds_read_b128 v[192:195], v179 offset:3072
	ds_read_b128 v[196:199], v179 offset:4096
	ds_read_b128 v[202:205], v179 offset:5120
	ds_read_b128 v[206:209], v179 offset:6144
	ds_read_b128 v[210:213], v179 offset:7168
	s_waitcnt vmcnt(8)
	s_waitcnt lgkmcnt(0)
	s_barrier
	v_mfma_f32_16x16x32_bf16 v[124:127], v[128:131], v[180:183], v[124:127]
	v_mfma_f32_16x16x32_bf16 v[120:123], v[150:153], v[180:183], v[120:123]
	v_mfma_f32_16x16x32_bf16 v[108:111], v[128:131], v[188:191], v[108:111]
	v_mfma_f32_16x16x32_bf16 v[104:107], v[150:153], v[188:191], v[104:107]
	v_mfma_f32_16x16x32_bf16 v[92:95], v[128:131], v[196:199], v[92:95]
	v_mfma_f32_16x16x32_bf16 v[88:91], v[150:153], v[196:199], v[88:91]
	v_mfma_f32_16x16x32_bf16 v[76:79], v[128:131], v[206:209], v[76:79]
	v_mfma_f32_16x16x32_bf16 v[72:75], v[150:153], v[206:209], v[72:75]
	v_mfma_f32_16x16x32_bf16 v[124:127], v[146:149], v[184:187], v[124:127]
	v_mfma_f32_16x16x32_bf16 v[120:123], v[154:157], v[184:187], v[120:123]
	v_mfma_f32_16x16x32_bf16 v[108:111], v[146:149], v[192:195], v[108:111]
	v_mfma_f32_16x16x32_bf16 v[104:107], v[154:157], v[192:195], v[104:107]
	v_mfma_f32_16x16x32_bf16 v[92:95], v[146:149], v[202:205], v[92:95]
	v_mfma_f32_16x16x32_bf16 v[88:91], v[154:157], v[202:205], v[88:91]
	v_mfma_f32_16x16x32_bf16 v[76:79], v[146:149], v[210:213], v[76:79]
	v_mfma_f32_16x16x32_bf16 v[72:75], v[154:157], v[210:213], v[72:75]
	v_mfma_f32_16x16x32_bf16 v[116:119], v[158:161], v[180:183], v[116:119]
	v_mfma_f32_16x16x32_bf16 v[112:115], v[166:169], v[180:183], v[112:115]
	v_mfma_f32_16x16x32_bf16 v[100:103], v[158:161], v[188:191], v[100:103]
	v_mfma_f32_16x16x32_bf16 v[96:99], v[166:169], v[188:191], v[96:99]
	v_mfma_f32_16x16x32_bf16 v[84:87], v[158:161], v[196:199], v[84:87]
	v_mfma_f32_16x16x32_bf16 v[80:83], v[166:169], v[196:199], v[80:83]
	v_mfma_f32_16x16x32_bf16 v[68:71], v[158:161], v[206:209], v[68:71]
	v_mfma_f32_16x16x32_bf16 v[64:67], v[166:169], v[206:209], v[64:67]
	v_mfma_f32_16x16x32_bf16 v[116:119], v[162:165], v[184:187], v[116:119]
	v_mfma_f32_16x16x32_bf16 v[112:115], v[170:173], v[184:187], v[112:115]
	v_mfma_f32_16x16x32_bf16 v[100:103], v[162:165], v[192:195], v[100:103]
	v_mfma_f32_16x16x32_bf16 v[96:99], v[170:173], v[192:195], v[96:99]
	v_mfma_f32_16x16x32_bf16 v[84:87], v[162:165], v[202:205], v[84:87]
	v_mfma_f32_16x16x32_bf16 v[80:83], v[170:173], v[202:205], v[80:83]
	v_mfma_f32_16x16x32_bf16 v[68:71], v[162:165], v[210:213], v[68:71]
	v_mfma_f32_16x16x32_bf16 v[64:67], v[170:173], v[210:213], v[64:67]
	s_barrier
	s_add_u32 s42, s46, 0x2b0000
	s_addc_u32 s43, s47, 0
	s_add_i32 m0, s50, 0x10000
	s_nop 0
	global_load_lds_dwordx4 v134, s[46:47]
	s_add_i32 m0, s50, 0x12000
	s_nop 0
	global_load_lds_dwordx4 v138, s[46:47]
	s_add_i32 m0, s50, 0x14000
	s_nop 0
	global_load_lds_dwordx4 v134, s[42:43]
	s_add_i32 m0, s50, 0x16000
	s_nop 0
	global_load_lds_dwordx4 v138, s[42:43]
	s_add_i32 m0, s50, 0x0
	s_nop 0
	global_load_lds_dwordx4 v132, s[48:49]
	s_add_i32 m0, s50, 0x2000
	s_nop 0
	global_load_lds_dwordx4 v136, s[48:49]
	ds_read_b128 v[180:183], v179 offset:16384
	ds_read_b128 v[184:187], v179 offset:17408
	ds_read_b128 v[188:191], v179 offset:18432
	ds_read_b128 v[192:195], v179 offset:19456
	ds_read_b128 v[196:199], v179 offset:20480
	ds_read_b128 v[202:205], v179 offset:21504
	ds_read_b128 v[206:209], v179 offset:22528
	ds_read_b128 v[210:213], v179 offset:23552
	s_waitcnt vmcnt(8)
	s_waitcnt lgkmcnt(0)
	s_barrier
	v_mfma_f32_16x16x32_bf16 v[60:63], v[128:131], v[180:183], v[60:63]
	v_mfma_f32_16x16x32_bf16 v[56:59], v[150:153], v[180:183], v[56:59]
	v_mfma_f32_16x16x32_bf16 v[44:47], v[128:131], v[188:191], v[44:47]
	v_mfma_f32_16x16x32_bf16 v[40:43], v[150:153], v[188:191], v[40:43]
	v_mfma_f32_16x16x32_bf16 v[28:31], v[128:131], v[196:199], v[28:31]
	v_mfma_f32_16x16x32_bf16 v[24:27], v[150:153], v[196:199], v[24:27]
	v_mfma_f32_16x16x32_bf16 v[12:15], v[128:131], v[206:209], v[12:15]
	v_mfma_f32_16x16x32_bf16 v[8:11], v[150:153], v[206:209], v[8:11]
	v_mfma_f32_16x16x32_bf16 v[60:63], v[146:149], v[184:187], v[60:63]
	v_mfma_f32_16x16x32_bf16 v[56:59], v[154:157], v[184:187], v[56:59]
	v_mfma_f32_16x16x32_bf16 v[44:47], v[146:149], v[192:195], v[44:47]
	v_mfma_f32_16x16x32_bf16 v[40:43], v[154:157], v[192:195], v[40:43]
	v_mfma_f32_16x16x32_bf16 v[28:31], v[146:149], v[202:205], v[28:31]
	v_mfma_f32_16x16x32_bf16 v[24:27], v[154:157], v[202:205], v[24:27]
	v_mfma_f32_16x16x32_bf16 v[12:15], v[146:149], v[210:213], v[12:15]
	v_mfma_f32_16x16x32_bf16 v[8:11], v[154:157], v[210:213], v[8:11]
	v_mfma_f32_16x16x32_bf16 v[52:55], v[158:161], v[180:183], v[52:55]
	v_mfma_f32_16x16x32_bf16 v[48:51], v[166:169], v[180:183], v[48:51]
	v_mfma_f32_16x16x32_bf16 v[36:39], v[158:161], v[188:191], v[36:39]
	v_mfma_f32_16x16x32_bf16 v[32:35], v[166:169], v[188:191], v[32:35]
	v_mfma_f32_16x16x32_bf16 v[20:23], v[158:161], v[196:199], v[20:23]
	v_mfma_f32_16x16x32_bf16 v[16:19], v[166:169], v[196:199], v[16:19]
	v_mfma_f32_16x16x32_bf16 v[4:7], v[158:161], v[206:209], v[4:7]
	v_mfma_f32_16x16x32_bf16 v[0:3], v[166:169], v[206:209], v[0:3]
	v_mfma_f32_16x16x32_bf16 v[52:55], v[162:165], v[184:187], v[52:55]
	v_mfma_f32_16x16x32_bf16 v[48:51], v[170:173], v[184:187], v[48:51]
	v_mfma_f32_16x16x32_bf16 v[36:39], v[162:165], v[192:195], v[36:39]
	v_mfma_f32_16x16x32_bf16 v[32:35], v[170:173], v[192:195], v[32:35]
	v_mfma_f32_16x16x32_bf16 v[20:23], v[162:165], v[202:205], v[20:23]
	v_mfma_f32_16x16x32_bf16 v[16:19], v[170:173], v[202:205], v[16:19]
	v_mfma_f32_16x16x32_bf16 v[4:7], v[162:165], v[210:213], v[4:7]
	v_mfma_f32_16x16x32_bf16 v[0:3], v[170:173], v[210:213], v[0:3]
	s_barrier
	s_add_u32 s98, s48, 0x2b0000
	s_addc_u32 s99, s49, 0
	s_add_i32 m0, s50, 0x4000
	s_nop 0
	global_load_lds_dwordx4 v132, s[98:99]
	s_add_i32 m0, s50, 0x6000
	s_nop 0
	global_load_lds_dwordx4 v136, s[98:99]
	ds_read_b128 v[128:131], v177 offset:32768
	ds_read_b128 v[146:149], v177 offset:33792
	ds_read_b128 v[150:153], v177 offset:34816
	ds_read_b128 v[154:157], v177 offset:35840
	ds_read_b128 v[158:161], v178 offset:32768
	ds_read_b128 v[162:165], v178 offset:33792
	ds_read_b128 v[166:169], v178 offset:34816
	ds_read_b128 v[170:173], v178 offset:35840
	ds_read_b128 v[180:183], v179 offset:32768
	ds_read_b128 v[184:187], v179 offset:33792
	ds_read_b128 v[188:191], v179 offset:34816
	ds_read_b128 v[192:195], v179 offset:35840
	ds_read_b128 v[196:199], v179 offset:36864
	ds_read_b128 v[202:205], v179 offset:37888
	ds_read_b128 v[206:209], v179 offset:38912
	ds_read_b128 v[210:213], v179 offset:39936
	s_waitcnt vmcnt(8)
	s_waitcnt lgkmcnt(0)
	s_barrier
	v_mfma_f32_16x16x32_bf16 v[124:127], v[128:131], v[180:183], v[124:127]
	v_mfma_f32_16x16x32_bf16 v[120:123], v[150:153], v[180:183], v[120:123]
	v_mfma_f32_16x16x32_bf16 v[108:111], v[128:131], v[188:191], v[108:111]
	v_mfma_f32_16x16x32_bf16 v[104:107], v[150:153], v[188:191], v[104:107]
	v_mfma_f32_16x16x32_bf16 v[92:95], v[128:131], v[196:199], v[92:95]
	v_mfma_f32_16x16x32_bf16 v[88:91], v[150:153], v[196:199], v[88:91]
	v_mfma_f32_16x16x32_bf16 v[76:79], v[128:131], v[206:209], v[76:79]
	v_mfma_f32_16x16x32_bf16 v[72:75], v[150:153], v[206:209], v[72:75]
	v_mfma_f32_16x16x32_bf16 v[124:127], v[146:149], v[184:187], v[124:127]
	v_mfma_f32_16x16x32_bf16 v[120:123], v[154:157], v[184:187], v[120:123]
	v_mfma_f32_16x16x32_bf16 v[108:111], v[146:149], v[192:195], v[108:111]
	v_mfma_f32_16x16x32_bf16 v[104:107], v[154:157], v[192:195], v[104:107]
	v_mfma_f32_16x16x32_bf16 v[92:95], v[146:149], v[202:205], v[92:95]
	v_mfma_f32_16x16x32_bf16 v[88:91], v[154:157], v[202:205], v[88:91]
	v_mfma_f32_16x16x32_bf16 v[76:79], v[146:149], v[210:213], v[76:79]
	v_mfma_f32_16x16x32_bf16 v[72:75], v[154:157], v[210:213], v[72:75]
	v_mfma_f32_16x16x32_bf16 v[116:119], v[158:161], v[180:183], v[116:119]
	v_mfma_f32_16x16x32_bf16 v[112:115], v[166:169], v[180:183], v[112:115]
	v_mfma_f32_16x16x32_bf16 v[100:103], v[158:161], v[188:191], v[100:103]
	v_mfma_f32_16x16x32_bf16 v[96:99], v[166:169], v[188:191], v[96:99]
	v_mfma_f32_16x16x32_bf16 v[84:87], v[158:161], v[196:199], v[84:87]
	v_mfma_f32_16x16x32_bf16 v[80:83], v[166:169], v[196:199], v[80:83]
	v_mfma_f32_16x16x32_bf16 v[68:71], v[158:161], v[206:209], v[68:71]
	v_mfma_f32_16x16x32_bf16 v[64:67], v[166:169], v[206:209], v[64:67]
	v_mfma_f32_16x16x32_bf16 v[116:119], v[162:165], v[184:187], v[116:119]
	v_mfma_f32_16x16x32_bf16 v[112:115], v[170:173], v[184:187], v[112:115]
	v_mfma_f32_16x16x32_bf16 v[100:103], v[162:165], v[192:195], v[100:103]
	v_mfma_f32_16x16x32_bf16 v[96:99], v[170:173], v[192:195], v[96:99]
	v_mfma_f32_16x16x32_bf16 v[84:87], v[162:165], v[202:205], v[84:87]
	v_mfma_f32_16x16x32_bf16 v[80:83], v[170:173], v[202:205], v[80:83]
	v_mfma_f32_16x16x32_bf16 v[68:71], v[162:165], v[210:213], v[68:71]
	v_mfma_f32_16x16x32_bf16 v[64:67], v[170:173], v[210:213], v[64:67]
	s_barrier
	s_add_u32 s100, s46, 0x80
	s_addc_u32 s101, s47, 0
	s_add_u32 s42, s46, 0x2b0080
	s_addc_u32 s43, s47, 0
	s_add_u32 s98, s48, 0x80
	s_addc_u32 s99, s49, 0
	s_add_i32 m0, s50, 0x18000
	s_nop 0
	global_load_lds_dwordx4 v134, s[100:101]
	s_add_i32 m0, s50, 0x1a000
	s_nop 0
	global_load_lds_dwordx4 v138, s[100:101]
	s_add_i32 m0, s50, 0x1c000
	s_nop 0
	global_load_lds_dwordx4 v134, s[42:43]
	s_add_i32 m0, s50, 0x1e000
	s_nop 0
	global_load_lds_dwordx4 v138, s[42:43]
	s_add_i32 m0, s50, 0x8000
	s_nop 0
	global_load_lds_dwordx4 v132, s[98:99]
	s_add_i32 m0, s50, 0xa000
	s_nop 0
	global_load_lds_dwordx4 v136, s[98:99]
	ds_read_b128 v[180:183], v179 offset:49152
	ds_read_b128 v[184:187], v179 offset:50176
	ds_read_b128 v[188:191], v179 offset:51200
	ds_read_b128 v[192:195], v179 offset:52224
	ds_read_b128 v[196:199], v179 offset:53248
	ds_read_b128 v[202:205], v179 offset:54272
	ds_read_b128 v[206:209], v179 offset:55296
	ds_read_b128 v[210:213], v179 offset:56320
	s_waitcnt vmcnt(8)
	s_waitcnt lgkmcnt(0)
	s_barrier
	v_mfma_f32_16x16x32_bf16 v[60:63], v[128:131], v[180:183], v[60:63]
	v_mfma_f32_16x16x32_bf16 v[56:59], v[150:153], v[180:183], v[56:59]
	v_mfma_f32_16x16x32_bf16 v[44:47], v[128:131], v[188:191], v[44:47]
	v_mfma_f32_16x16x32_bf16 v[40:43], v[150:153], v[188:191], v[40:43]
	v_mfma_f32_16x16x32_bf16 v[28:31], v[128:131], v[196:199], v[28:31]
	v_mfma_f32_16x16x32_bf16 v[24:27], v[150:153], v[196:199], v[24:27]
	v_mfma_f32_16x16x32_bf16 v[12:15], v[128:131], v[206:209], v[12:15]
	v_mfma_f32_16x16x32_bf16 v[8:11], v[150:153], v[206:209], v[8:11]
	v_mfma_f32_16x16x32_bf16 v[60:63], v[146:149], v[184:187], v[60:63]
	v_mfma_f32_16x16x32_bf16 v[56:59], v[154:157], v[184:187], v[56:59]
	v_mfma_f32_16x16x32_bf16 v[44:47], v[146:149], v[192:195], v[44:47]
	v_mfma_f32_16x16x32_bf16 v[40:43], v[154:157], v[192:195], v[40:43]
	v_mfma_f32_16x16x32_bf16 v[28:31], v[146:149], v[202:205], v[28:31]
	v_mfma_f32_16x16x32_bf16 v[24:27], v[154:157], v[202:205], v[24:27]
	v_mfma_f32_16x16x32_bf16 v[12:15], v[146:149], v[210:213], v[12:15]
	v_mfma_f32_16x16x32_bf16 v[8:11], v[154:157], v[210:213], v[8:11]
	v_mfma_f32_16x16x32_bf16 v[52:55], v[158:161], v[180:183], v[52:55]
	v_mfma_f32_16x16x32_bf16 v[48:51], v[166:169], v[180:183], v[48:51]
	v_mfma_f32_16x16x32_bf16 v[36:39], v[158:161], v[188:191], v[36:39]
	v_mfma_f32_16x16x32_bf16 v[32:35], v[166:169], v[188:191], v[32:35]
	v_mfma_f32_16x16x32_bf16 v[20:23], v[158:161], v[196:199], v[20:23]
	v_mfma_f32_16x16x32_bf16 v[16:19], v[166:169], v[196:199], v[16:19]
	v_mfma_f32_16x16x32_bf16 v[4:7], v[158:161], v[206:209], v[4:7]
	v_mfma_f32_16x16x32_bf16 v[0:3], v[166:169], v[206:209], v[0:3]
	v_mfma_f32_16x16x32_bf16 v[52:55], v[162:165], v[184:187], v[52:55]
	v_mfma_f32_16x16x32_bf16 v[48:51], v[170:173], v[184:187], v[48:51]
	v_mfma_f32_16x16x32_bf16 v[36:39], v[162:165], v[192:195], v[36:39]
	v_mfma_f32_16x16x32_bf16 v[32:35], v[170:173], v[192:195], v[32:35]
	v_mfma_f32_16x16x32_bf16 v[20:23], v[162:165], v[202:205], v[20:23]
	v_mfma_f32_16x16x32_bf16 v[16:19], v[170:173], v[202:205], v[16:19]
	v_mfma_f32_16x16x32_bf16 v[4:7], v[162:165], v[210:213], v[4:7]
	v_mfma_f32_16x16x32_bf16 v[0:3], v[170:173], v[210:213], v[0:3]
	s_barrier
	s_add_u32 s68, s68, 0x100
	s_addc_u32 s69, s69, 0
	s_cmp_ge_i32 s70, s67
	s_mov_b64 s[42:43], s[44:45]
	s_mov_b32 s46, s70
	s_cbranch_scc0 .LBB0_1409
	s_and_b64 vcc, exec, s[14:15]
	s_cbranch_vccz .LBB0_1412
